# P2 reordered: conv31 runs before the scores GEMM so P tiles are consumed by P-V right after being written; P1 K-loop LDS-DMA loads use SGPR-base addressing (no per-load VALU adds)
# speedup vs baseline: 1.0553x; 1.0074x over previous
; #define GP_STAGE(bufoff, gbase, voff) do { _Pragma("unroll") for (int _i = 0; _i < 2; ++_i) \
;         __builtin_amdgcn_global_load_lds((const unsigned*)((const char*)(gbase) + (voff)[_i]), (LAS unsigned*)(lds + (bufoff) + ldsw + _i * 8192), 16, 0, 0); } while (0)
; #define GP_LDA(dst, b, h) do { _Pragma("unroll") for (int m = 0; m < 4; ++m) _Pragma("unroll") for (int k = 0; k < 2; ++k) dst[m][k] = *(const LAS bf16x8*)(lds + GP_SA(b, h) + aoff + m * 2048 + k * 1024); } while (0)
; #define GP_LDB(dst, b, h) do { _Pragma("unroll") for (int n = 0; n < 2; ++n) _Pragma("unroll") for (int k = 0; k < 2; ++k) dst[n][k] = *(const LAS bf16x8*)(lds + GP_SB(b, h) + boff + n * 2048 + k * 1024); } while (0)
; #define GP_MMA(ai, bj, At, Bt) do { __builtin_amdgcn_s_setprio(1); _Pragma("unroll") for (int m = 0; m < 4; ++m) _Pragma("unroll") for (int n = 0; n < 2; ++n) _Pragma("unroll") for (int k = 0; k < 2; ++k) \
;         acc[ai][bj][m][n] = __builtin_amdgcn_mfma_f32_16x16x32_bf16(Bt[n][k], At[m][k], acc[ai][bj][m][n], 0, 0, 0); __builtin_amdgcn_s_setprio(0); } while (0)
; #define GP_WAIT_V(n) asm volatile("s_waitcnt vmcnt(" #n ")" ::: "memory")
; #define GP_WAIT_L(n) asm volatile("s_waitcnt lgkmcnt(" #n ")" ::: "memory")
; #define GP_BAR __builtin_amdgcn_s_barrier()
; #define GP_SCHED __builtin_amdgcn_sched_barrier(0)
; template <class Epi, class Sched>
; __device__ __forceinline__ void gemm_phase(LAS unsigned char* lds, const int lda, const int ldb, const int K, const Sched& S, const Epi& E, const int widx) {
;     ...
;             GP_LDB(B0, 0, 0); GP_LDB(B1, 0, 1); GP_SCHED; GP_LDA(At, 0, 0); GP_STAGE(GP_SA(1, 1), a1 + hstepA, voffA);
;             GP_WAIT_V(8); GP_WAIT_L(0); GP_BAR; GP_MMA(0, 0, At, B0); GP_MMA(0, 1, At, B1); GP_BAR; GP_SCHED;
;             GP_LDA(At, 0, 1); GP_STAGE(GP_SB(0, 0), b2, voffB); GP_STAGE(GP_SB(0, 1), b2 + hstepB, voffB); GP_STAGE(GP_SA(0, 0), a2, voffA);
;             GP_WAIT_V(8); GP_WAIT_L(0); GP_BAR; GP_MMA(1, 0, At, B0); GP_MMA(1, 1, At, B1); GP_BAR; GP_SCHED;
.LBB0_135:
	v_add_u32_e32 v144, s55, v167
	ds_read_b128 v[128:131], v144
	ds_read_b128 v[132:135], v144 offset:1024
	ds_read_b128 v[136:139], v144 offset:2048
	ds_read_b128 v[174:177], v144 offset:3072
	v_add_u32_e32 v144, s79, v167
	ds_read_b128 v[178:181], v144
	ds_read_b128 v[182:185], v144 offset:1024
	ds_read_b128 v[186:189], v144 offset:2048
	ds_read_b128 v[190:193], v144 offset:3072
	s_add_u32 s30, s4, 0xfffc0080
	s_addc_u32 s31, s5, -1
	s_cmp_eq_u32 s83, 12
	s_cselect_b32 s31, s35, s31
	s_cselect_b32 s30, s42, s30
	s_cselect_b32 s93, s43, s82
	s_cselect_b32 s92, s64, s81
	s_add_i32 m0, s85, 0xc000
	ds_read_b128 v[198:201], v196
	ds_read_b128 v[202:205], v196 offset:1024
	ds_read_b128 v[206:209], v196 offset:2048
	ds_read_b128 v[210:213], v196 offset:3072
	ds_read_b128 v[214:217], v196 offset:4096
	ds_read_b128 v[218:221], v196 offset:5120
	ds_read_b128 v[222:225], v196 offset:6144
	ds_read_b128 v[226:229], v196 offset:7168
	global_load_lds_dwordx4 v170, s[4:5]
	s_add_i32 m0, s85, 0xe000
	s_nop 0
	global_load_lds_dwordx4 v172, s[4:5]
	s_waitcnt vmcnt(8)
	s_waitcnt lgkmcnt(0)
	s_barrier
	s_setprio 1
	s_waitcnt lgkmcnt(0)
	v_mfma_f32_16x16x32_bf16 v[116:119], v[128:131], v[198:201], v[116:119]
	v_mfma_f32_16x16x32_bf16 v[124:127], v[136:139], v[198:201], v[124:127]
	v_mfma_f32_16x16x32_bf16 v[84:87], v[128:131], v[206:209], v[84:87]
	v_mfma_f32_16x16x32_bf16 v[108:111], v[136:139], v[206:209], v[108:111]
	v_mfma_f32_16x16x32_bf16 v[76:79], v[128:131], v[214:217], v[76:79]
	v_mfma_f32_16x16x32_bf16 v[100:103], v[136:139], v[214:217], v[100:103]
	v_mfma_f32_16x16x32_bf16 v[68:71], v[128:131], v[222:225], v[68:71]
	v_mfma_f32_16x16x32_bf16 v[92:95], v[136:139], v[222:225], v[92:95]
	v_mfma_f32_16x16x32_bf16 v[116:119], v[132:135], v[202:205], v[116:119]
	v_mfma_f32_16x16x32_bf16 v[124:127], v[174:177], v[202:205], v[124:127]
	v_mfma_f32_16x16x32_bf16 v[84:87], v[132:135], v[210:213], v[84:87]
	v_mfma_f32_16x16x32_bf16 v[108:111], v[174:177], v[210:213], v[108:111]
	v_mfma_f32_16x16x32_bf16 v[76:79], v[132:135], v[218:221], v[76:79]
	v_mfma_f32_16x16x32_bf16 v[100:103], v[174:177], v[218:221], v[100:103]
	v_mfma_f32_16x16x32_bf16 v[68:71], v[132:135], v[226:229], v[68:71]
	v_mfma_f32_16x16x32_bf16 v[92:95], v[174:177], v[226:229], v[92:95]
	s_setprio 0
	s_setprio 1
	v_mfma_f32_16x16x32_bf16 v[120:123], v[178:181], v[198:201], v[120:123]
	v_mfma_f32_16x16x32_bf16 v[112:115], v[186:189], v[198:201], v[112:115]
	v_mfma_f32_16x16x32_bf16 v[104:107], v[178:181], v[206:209], v[104:107]
	v_mfma_f32_16x16x32_bf16 v[80:83], v[186:189], v[206:209], v[80:83]
	v_mfma_f32_16x16x32_bf16 v[96:99], v[178:181], v[214:217], v[96:99]
	v_mfma_f32_16x16x32_bf16 v[72:75], v[186:189], v[214:217], v[72:75]
	v_mfma_f32_16x16x32_bf16 v[88:91], v[178:181], v[222:225], v[88:91]
	v_mfma_f32_16x16x32_bf16 v[64:67], v[186:189], v[222:225], v[64:67]
	v_mfma_f32_16x16x32_bf16 v[120:123], v[182:185], v[202:205], v[120:123]
	v_mfma_f32_16x16x32_bf16 v[112:115], v[190:193], v[202:205], v[112:115]
	v_mfma_f32_16x16x32_bf16 v[104:107], v[182:185], v[210:213], v[104:107]
	v_mfma_f32_16x16x32_bf16 v[80:83], v[190:193], v[210:213], v[80:83]
	v_mfma_f32_16x16x32_bf16 v[96:99], v[182:185], v[218:221], v[96:99]
	v_mfma_f32_16x16x32_bf16 v[72:75], v[190:193], v[218:221], v[72:75]
	v_mfma_f32_16x16x32_bf16 v[88:91], v[182:185], v[226:229], v[88:91]
	v_mfma_f32_16x16x32_bf16 v[64:67], v[190:193], v[226:229], v[64:67]
	s_setprio 0
	s_barrier
	s_add_i32 s86, s55, s97
	s_mov_b32 m0, s86
	ds_read_b128 v[198:201], v196 offset:16384
	ds_read_b128 v[202:205], v196 offset:17408
	ds_read_b128 v[206:209], v196 offset:18432
	ds_read_b128 v[210:213], v196 offset:19456
	ds_read_b128 v[214:217], v196 offset:20480
	ds_read_b128 v[218:221], v196 offset:21504
	ds_read_b128 v[222:225], v196 offset:22528
	ds_read_b128 v[226:229], v196 offset:23552
	global_load_lds_dwordx4 v140, s[92:93]
	s_add_i32 m0, s86, 0x2000
	s_add_u32 s86, s92, 0x40000
	s_addc_u32 s87, s93, 0
	s_add_i32 s88, s79, s97
	global_load_lds_dwordx4 v142, s[92:93]
	s_mov_b32 m0, s88
	s_nop 0
	global_load_lds_dwordx4 v140, s[86:87]
	s_add_i32 m0, s88, 0x2000
	s_nop 0
	global_load_lds_dwordx4 v142, s[86:87]
	s_mov_b32 m0, s85
	s_nop 0
	global_load_lds_dwordx4 v140, s[30:31]
	s_mov_b32 m0, s33
	s_nop 0
	global_load_lds_dwordx4 v142, s[30:31]
	s_add_u32 s100, s30, 0x80
	s_addc_u32 s101, s31, 0
	s_waitcnt vmcnt(8)
	s_waitcnt lgkmcnt(0)
	s_barrier
	s_setprio 1
	s_waitcnt lgkmcnt(0)
	v_mfma_f32_16x16x32_bf16 v[52:55], v[128:131], v[198:201], v[52:55]
	v_mfma_f32_16x16x32_bf16 v[60:63], v[136:139], v[198:201], v[60:63]
	v_mfma_f32_16x16x32_bf16 v[20:23], v[128:131], v[206:209], v[20:23]
	v_mfma_f32_16x16x32_bf16 v[44:47], v[136:139], v[206:209], v[44:47]
	v_mfma_f32_16x16x32_bf16 v[12:15], v[128:131], v[214:217], v[12:15]
	v_mfma_f32_16x16x32_bf16 v[36:39], v[136:139], v[214:217], v[36:39]
	v_mfma_f32_16x16x32_bf16 v[4:7], v[128:131], v[222:225], v[4:7]
	v_mfma_f32_16x16x32_bf16 v[28:31], v[136:139], v[222:225], v[28:31]
	v_mfma_f32_16x16x32_bf16 v[52:55], v[132:135], v[202:205], v[52:55]
	v_mfma_f32_16x16x32_bf16 v[60:63], v[174:177], v[202:205], v[60:63]
	v_mfma_f32_16x16x32_bf16 v[20:23], v[132:135], v[210:213], v[20:23]
	v_mfma_f32_16x16x32_bf16 v[44:47], v[174:177], v[210:213], v[44:47]
	v_mfma_f32_16x16x32_bf16 v[12:15], v[132:135], v[218:221], v[12:15]
	v_mfma_f32_16x16x32_bf16 v[36:39], v[174:177], v[218:221], v[36:39]
	v_mfma_f32_16x16x32_bf16 v[4:7], v[132:135], v[226:229], v[4:7]
	v_mfma_f32_16x16x32_bf16 v[28:31], v[174:177], v[226:229], v[28:31]
	s_setprio 0
	s_setprio 1
	v_mfma_f32_16x16x32_bf16 v[56:59], v[178:181], v[198:201], v[56:59]
	v_mfma_f32_16x16x32_bf16 v[48:51], v[186:189], v[198:201], v[48:51]
	v_mfma_f32_16x16x32_bf16 v[40:43], v[178:181], v[206:209], v[40:43]
	v_mfma_f32_16x16x32_bf16 v[16:19], v[186:189], v[206:209], v[16:19]
	v_mfma_f32_16x16x32_bf16 v[32:35], v[178:181], v[214:217], v[32:35]
	v_mfma_f32_16x16x32_bf16 v[8:11], v[186:189], v[214:217], v[8:11]
	v_mfma_f32_16x16x32_bf16 v[24:27], v[178:181], v[222:225], v[24:27]
	v_mfma_f32_16x16x32_bf16 v[0:3], v[186:189], v[222:225], v[0:3]
	v_mfma_f32_16x16x32_bf16 v[56:59], v[182:185], v[202:205], v[56:59]
	v_mfma_f32_16x16x32_bf16 v[48:51], v[190:193], v[202:205], v[48:51]
	v_mfma_f32_16x16x32_bf16 v[40:43], v[182:185], v[210:213], v[40:43]
	v_mfma_f32_16x16x32_bf16 v[16:19], v[190:193], v[210:213], v[16:19]
	v_mfma_f32_16x16x32_bf16 v[32:35], v[182:185], v[218:221], v[32:35]
	v_mfma_f32_16x16x32_bf16 v[8:11], v[190:193], v[218:221], v[8:11]
	v_mfma_f32_16x16x32_bf16 v[24:27], v[182:185], v[226:229], v[24:27]
	v_mfma_f32_16x16x32_bf16 v[0:3], v[190:193], v[226:229], v[0:3]
	s_setprio 0
	s_barrier
; #define GP_STAGE(bufoff, gbase, voff) do { _Pragma("unroll") for (int _i = 0; _i < 2; ++_i) \
;         __builtin_amdgcn_global_load_lds((const unsigned*)((const char*)(gbase) + (voff)[_i]), (LAS unsigned*)(lds + (bufoff) + ldsw + _i * 8192), 16, 0, 0); } while (0)
; #define GP_LDA(dst, b, h) do { _Pragma("unroll") for (int m = 0; m < 4; ++m) _Pragma("unroll") for (int k = 0; k < 2; ++k) dst[m][k] = *(const LAS bf16x8*)(lds + GP_SA(b, h) + aoff + m * 2048 + k * 1024); } while (0)
; #define GP_LDB(dst, b, h) do { _Pragma("unroll") for (int n = 0; n < 2; ++n) _Pragma("unroll") for (int k = 0; k < 2; ++k) dst[n][k] = *(const LAS bf16x8*)(lds + GP_SB(b, h) + boff + n * 2048 + k * 1024); } while (0)
; #define GP_MMA(ai, bj, At, Bt) do { __builtin_amdgcn_s_setprio(1); _Pragma("unroll") for (int m = 0; m < 4; ++m) _Pragma("unroll") for (int n = 0; n < 2; ++n) _Pragma("unroll") for (int k = 0; k < 2; ++k) \
;         acc[ai][bj][m][n] = __builtin_amdgcn_mfma_f32_16x16x32_bf16(Bt[n][k], At[m][k], acc[ai][bj][m][n], 0, 0, 0); __builtin_amdgcn_s_setprio(0); } while (0)
; #define GP_WAIT_V(n) asm volatile("s_waitcnt vmcnt(" #n ")" ::: "memory")
; #define GP_WAIT_L(n) asm volatile("s_waitcnt lgkmcnt(" #n ")" ::: "memory")
; #define GP_BAR __builtin_amdgcn_s_barrier()
; #define GP_SCHED __builtin_amdgcn_sched_barrier(0)
; template <class Epi, class Sched>
; __device__ __forceinline__ void gemm_phase(LAS unsigned char* lds, const int lda, const int ldb, const int K, const Sched& S, const Epi& E, const int widx) {
;     ...
;             GP_LDB(B0, 1, 0); GP_LDB(B1, 1, 1); GP_SCHED; GP_LDA(At, 1, 0); GP_STAGE(GP_SA(0, 1), a2 + hstepA, voffA);
;             GP_WAIT_V(8); GP_WAIT_L(0); GP_BAR; GP_MMA(0, 0, At, B0); GP_MMA(0, 1, At, B1); GP_BAR; GP_SCHED;
;             GP_LDA(At, 1, 1); GP_STAGE(GP_SB(1, 0), b3, voffB); GP_STAGE(GP_SB(1, 1), b3 + hstepB, voffB); GP_STAGE(GP_SA(1, 0), a3, voffA);
;             GP_WAIT_V(8); GP_WAIT_L(0); GP_BAR; GP_MMA(1, 0, At, B0); GP_MMA(1, 1, At, B1); GP_BAR; GP_SCHED;
;         }
	s_add_i32 s86, 0, 0x18000
	v_add_u32_e32 v144, s86, v167
	s_add_i32 s87, 0, 0x1c000
	ds_read_b128 v[128:131], v144
	ds_read_b128 v[132:135], v144 offset:1024
	ds_read_b128 v[136:139], v144 offset:2048
	ds_read_b128 v[174:177], v144 offset:3072
	v_add_u32_e32 v144, s87, v167
	ds_read_b128 v[178:181], v144
	ds_read_b128 v[182:185], v144 offset:1024
	ds_read_b128 v[186:189], v144 offset:2048
	ds_read_b128 v[190:193], v144 offset:3072
	s_add_u32 s30, s30, 0x40000
	s_addc_u32 s31, s31, 0
	s_mov_b32 m0, s74
	ds_read_b128 v[198:201], v196 offset:32768
	ds_read_b128 v[202:205], v196 offset:33792
	ds_read_b128 v[206:209], v196 offset:34816
	ds_read_b128 v[210:213], v196 offset:35840
	ds_read_b128 v[214:217], v196 offset:36864
	ds_read_b128 v[218:221], v196 offset:37888
	ds_read_b128 v[222:225], v196 offset:38912
	ds_read_b128 v[226:229], v196 offset:39936
	global_load_lds_dwordx4 v140, s[30:31]
	s_mov_b32 m0, s75
	s_nop 0
	global_load_lds_dwordx4 v142, s[30:31]
	s_waitcnt vmcnt(8)
	s_waitcnt lgkmcnt(0)
	s_barrier
	s_setprio 1
	s_waitcnt lgkmcnt(0)
	v_mfma_f32_16x16x32_bf16 v[116:119], v[128:131], v[198:201], v[116:119]
	v_mfma_f32_16x16x32_bf16 v[124:127], v[136:139], v[198:201], v[124:127]
	v_mfma_f32_16x16x32_bf16 v[84:87], v[128:131], v[206:209], v[84:87]
	v_mfma_f32_16x16x32_bf16 v[108:111], v[136:139], v[206:209], v[108:111]
	v_mfma_f32_16x16x32_bf16 v[76:79], v[128:131], v[214:217], v[76:79]
	v_mfma_f32_16x16x32_bf16 v[100:103], v[136:139], v[214:217], v[100:103]
	v_mfma_f32_16x16x32_bf16 v[68:71], v[128:131], v[222:225], v[68:71]
	v_mfma_f32_16x16x32_bf16 v[92:95], v[136:139], v[222:225], v[92:95]
	v_mfma_f32_16x16x32_bf16 v[116:119], v[132:135], v[202:205], v[116:119]
	v_mfma_f32_16x16x32_bf16 v[124:127], v[174:177], v[202:205], v[124:127]
	v_mfma_f32_16x16x32_bf16 v[84:87], v[132:135], v[210:213], v[84:87]
	v_mfma_f32_16x16x32_bf16 v[108:111], v[174:177], v[210:213], v[108:111]
	v_mfma_f32_16x16x32_bf16 v[76:79], v[132:135], v[218:221], v[76:79]
	v_mfma_f32_16x16x32_bf16 v[100:103], v[174:177], v[218:221], v[100:103]
	v_mfma_f32_16x16x32_bf16 v[68:71], v[132:135], v[226:229], v[68:71]
	v_mfma_f32_16x16x32_bf16 v[92:95], v[174:177], v[226:229], v[92:95]
	s_setprio 0
	s_setprio 1
	v_mfma_f32_16x16x32_bf16 v[120:123], v[178:181], v[198:201], v[120:123]
	v_mfma_f32_16x16x32_bf16 v[112:115], v[186:189], v[198:201], v[112:115]
	v_mfma_f32_16x16x32_bf16 v[104:107], v[178:181], v[206:209], v[104:107]
	v_mfma_f32_16x16x32_bf16 v[80:83], v[186:189], v[206:209], v[80:83]
	v_mfma_f32_16x16x32_bf16 v[96:99], v[178:181], v[214:217], v[96:99]
	v_mfma_f32_16x16x32_bf16 v[72:75], v[186:189], v[214:217], v[72:75]
	v_mfma_f32_16x16x32_bf16 v[88:91], v[178:181], v[222:225], v[88:91]
	v_mfma_f32_16x16x32_bf16 v[64:67], v[186:189], v[222:225], v[64:67]
	v_mfma_f32_16x16x32_bf16 v[120:123], v[182:185], v[202:205], v[120:123]
	v_mfma_f32_16x16x32_bf16 v[112:115], v[190:193], v[202:205], v[112:115]
	v_mfma_f32_16x16x32_bf16 v[104:107], v[182:185], v[210:213], v[104:107]
	v_mfma_f32_16x16x32_bf16 v[80:83], v[190:193], v[210:213], v[80:83]
	v_mfma_f32_16x16x32_bf16 v[96:99], v[182:185], v[218:221], v[96:99]
	v_mfma_f32_16x16x32_bf16 v[72:75], v[190:193], v[218:221], v[72:75]
	v_mfma_f32_16x16x32_bf16 v[88:91], v[182:185], v[226:229], v[88:91]
	v_mfma_f32_16x16x32_bf16 v[64:67], v[190:193], v[226:229], v[64:67]
	s_setprio 0
	s_barrier
	s_add_u32 s98, s92, 0x80
	s_addc_u32 s99, s93, 0
	s_add_i32 s30, s86, s97
	s_mov_b32 m0, s30
	ds_read_b128 v[198:201], v196 offset:49152
	ds_read_b128 v[202:205], v196 offset:50176
	ds_read_b128 v[206:209], v196 offset:51200
	ds_read_b128 v[210:213], v196 offset:52224
	ds_read_b128 v[214:217], v196 offset:53248
	ds_read_b128 v[218:221], v196 offset:54272
	ds_read_b128 v[222:225], v196 offset:55296
	ds_read_b128 v[226:229], v196 offset:56320
	global_load_lds_dwordx4 v140, s[98:99]
	s_add_i32 m0, s30, 0x2000
	s_add_u32 s30, s92, 0x40080
	s_addc_u32 s31, s93, 0
	s_add_i32 s86, s87, s97
	global_load_lds_dwordx4 v142, s[98:99]
	s_mov_b32 m0, s86
	s_nop 0
	global_load_lds_dwordx4 v140, s[30:31]
	s_add_i32 m0, s86, 0x2000
	s_nop 0
	global_load_lds_dwordx4 v142, s[30:31]
	s_mov_b32 m0, s76
	s_nop 0
	global_load_lds_dwordx4 v140, s[100:101]
	s_mov_b32 m0, s77
	s_nop 0
	global_load_lds_dwordx4 v142, s[100:101]
	s_waitcnt vmcnt(8)
	s_waitcnt lgkmcnt(0)
	s_barrier
	s_setprio 1
	s_waitcnt lgkmcnt(0)
	v_mfma_f32_16x16x32_bf16 v[52:55], v[128:131], v[198:201], v[52:55]
	v_mfma_f32_16x16x32_bf16 v[60:63], v[136:139], v[198:201], v[60:63]
	v_mfma_f32_16x16x32_bf16 v[20:23], v[128:131], v[206:209], v[20:23]
	v_mfma_f32_16x16x32_bf16 v[44:47], v[136:139], v[206:209], v[44:47]
	v_mfma_f32_16x16x32_bf16 v[12:15], v[128:131], v[214:217], v[12:15]
	v_mfma_f32_16x16x32_bf16 v[36:39], v[136:139], v[214:217], v[36:39]
	v_mfma_f32_16x16x32_bf16 v[4:7], v[128:131], v[222:225], v[4:7]
	v_mfma_f32_16x16x32_bf16 v[28:31], v[136:139], v[222:225], v[28:31]
	v_mfma_f32_16x16x32_bf16 v[52:55], v[132:135], v[202:205], v[52:55]
	v_mfma_f32_16x16x32_bf16 v[60:63], v[174:177], v[202:205], v[60:63]
	v_mfma_f32_16x16x32_bf16 v[20:23], v[132:135], v[210:213], v[20:23]
	v_mfma_f32_16x16x32_bf16 v[44:47], v[174:177], v[210:213], v[44:47]
	v_mfma_f32_16x16x32_bf16 v[12:15], v[132:135], v[218:221], v[12:15]
	v_mfma_f32_16x16x32_bf16 v[36:39], v[174:177], v[218:221], v[36:39]
	v_mfma_f32_16x16x32_bf16 v[4:7], v[132:135], v[226:229], v[4:7]
	v_mfma_f32_16x16x32_bf16 v[28:31], v[174:177], v[226:229], v[28:31]
	s_setprio 0
	s_setprio 1
	v_mfma_f32_16x16x32_bf16 v[56:59], v[178:181], v[198:201], v[56:59]
	v_mfma_f32_16x16x32_bf16 v[48:51], v[186:189], v[198:201], v[48:51]
	v_mfma_f32_16x16x32_bf16 v[40:43], v[178:181], v[206:209], v[40:43]
	v_mfma_f32_16x16x32_bf16 v[16:19], v[186:189], v[206:209], v[16:19]
	v_mfma_f32_16x16x32_bf16 v[32:35], v[178:181], v[214:217], v[32:35]
	v_mfma_f32_16x16x32_bf16 v[8:11], v[186:189], v[214:217], v[8:11]
	v_mfma_f32_16x16x32_bf16 v[24:27], v[178:181], v[222:225], v[24:27]
	v_mfma_f32_16x16x32_bf16 v[0:3], v[186:189], v[222:225], v[0:3]
	v_mfma_f32_16x16x32_bf16 v[56:59], v[182:185], v[202:205], v[56:59]
	v_mfma_f32_16x16x32_bf16 v[48:51], v[190:193], v[202:205], v[48:51]
	v_mfma_f32_16x16x32_bf16 v[40:43], v[182:185], v[210:213], v[40:43]
	v_mfma_f32_16x16x32_bf16 v[16:19], v[190:193], v[210:213], v[16:19]
	v_mfma_f32_16x16x32_bf16 v[32:35], v[182:185], v[218:221], v[32:35]
	v_mfma_f32_16x16x32_bf16 v[8:11], v[190:193], v[218:221], v[8:11]
	v_mfma_f32_16x16x32_bf16 v[24:27], v[182:185], v[226:229], v[24:27]
	v_mfma_f32_16x16x32_bf16 v[0:3], v[190:193], v[226:229], v[0:3]
	s_setprio 0
	s_barrier
	s_add_i32 s83, s83, 2
	s_add_u32 s4, s4, 0x100
	s_addc_u32 s5, s5, 0
	s_add_u32 s81, s81, 0x100
	s_addc_u32 s82, s82, 0
	s_cmp_gt_u32 s83, 13
	s_cbranch_scc0 .LBB0_135
	s_and_b64 vcc, exec, s[72:73]
	s_cbranch_vccz .LBB0_139
	s_barrier
	s_cmp_gt_i32 s13, 2
	s_mov_b64 s[4:5], -1
	s_cbranch_scc1 .LBB0_140

; #define LAS __attribute__((address_space(3)))
; template <int PH> ...
;     ...
;     const f32x2 bias = *(const f32x2*)(cb + c2);
;     f32x2 outv[16];
; #pragma unroll
;     for (int t = 0; t < 16; ++t) outv[t] = bias;
; #pragma unroll
;     for (int ps = 0; ps < 2; ++ps) {
;         const int kb = ps * 16, ntap = ps == 0 ? 16 : 15;
;         f32x2 w[16];
; #pragma unroll
;         for (int k = 0; k < 16; ++k) if (k < ntap) w[k] = *(const f32x2*)(cw + (kb + k) * 1024 + c2);
; __device__ __forceinline__ void conv31_phase(LAS unsigned char* lds, const bf16_t* GLU, bf16_t* SZB, const float* cw, const float* cb, const float* lng, const float* lnb, int G, int c, const int widx) {
;     ...
;     for (int run = c; run < NTOK / 128; run += G) {
;         const int T0 = run * 128, tpos = T0 & (SEQ - 1);
;         __syncthreads();
; #pragma unroll
;         for (int h = 0; h < 2; ++h) {
;             int tf = tid; asm volatile("" : "+v"(tf));
;             u32x4 tv[6];
; #pragma unroll
;             for (int q = 0; q < 6; ++q) { const int i = tf + (h * 6 + q) * 512, r = (i >> 7) < 46 ? (i >> 7) : 45; const int gr = (tpos - 30 + r >= 0) ? (T0 - 30 + r) : T0;
;                 tv[q] = *(const u32x4*)(GLU + (size_t)gr * 1024 + (i & 127) * 8); }
; #pragma unroll
;             for (int q = 0; q < 6; ++q) { const int i = tf + (h * 6 + q) * 512, r = i >> 7;
;                 if (r < 46) *(LAS u32x4*)(lds + ((34 + r) & 63) * 2048 + (i & 127) * 16) = (tpos - 30 + r >= 0) ? tv[q] : (u32x4){0u, 0u, 0u, 0u}; }
;         }
;         __syncthreads();
.LBB0_352:
	s_or_b64 exec, exec, s[0:1]
	v_mbcnt_lo_u32_b32 v224, -1, 0
	v_mbcnt_hi_u32_b32 v224, -1, v224
	s_cmpk_gt_i32 s2, 0xff
	s_cbranch_scc1 .Lc31_done
	v_add_u32_e32 v225, s87, v224
	v_lshlrev_b32_e32 v226, 2, v225
	v_lshlrev_b32_e32 v227, 3, v225
	v_mov_b32_e32 v254, 0
	v_lshrrev_b32_e32 v253, 4, v224
	v_lshlrev_b32_e32 v253, 7, v253
	s_lshr_b32 s4, s87, 3
	v_add_u32_e32 v253, s4, v253
	s_lshl_b32 s6, s2, 7
	s_mov_b32 s54, 0xbfb8aa3b
	s_mov_b32 s55, 0xbfb8aa3b
	s_mov_b64 s[100:101], s[48:49]
	global_load_dwordx2 v[92:93], v227, s[100:101]
	s_add_u32 s100, s100, 0x1000
	s_addc_u32 s101, s101, 0
	global_load_dwordx2 v[94:95], v227, s[100:101]
	s_add_u32 s100, s100, 0x1000
	s_addc_u32 s101, s101, 0
	global_load_dwordx2 v[96:97], v227, s[100:101]
	s_add_u32 s100, s100, 0x1000
	s_addc_u32 s101, s101, 0
	global_load_dwordx2 v[98:99], v227, s[100:101]
	s_add_u32 s100, s100, 0x1000
	s_addc_u32 s101, s101, 0
	global_load_dwordx2 v[100:101], v227, s[100:101]
	s_add_u32 s100, s100, 0x1000
	s_addc_u32 s101, s101, 0
	global_load_dwordx2 v[102:103], v227, s[100:101]
	s_add_u32 s100, s100, 0x1000
	s_addc_u32 s101, s101, 0
	global_load_dwordx2 v[104:105], v227, s[100:101]
	s_add_u32 s100, s100, 0x1000
	s_addc_u32 s101, s101, 0
	global_load_dwordx2 v[106:107], v227, s[100:101]
	s_add_u32 s100, s100, 0x1000
	s_addc_u32 s101, s101, 0
	global_load_dwordx2 v[108:109], v227, s[100:101]
	s_add_u32 s100, s100, 0x1000
	s_addc_u32 s101, s101, 0
	global_load_dwordx2 v[110:111], v227, s[100:101]
	s_add_u32 s100, s100, 0x1000
	s_addc_u32 s101, s101, 0
	global_load_dwordx2 v[112:113], v227, s[100:101]
	s_add_u32 s100, s100, 0x1000
	s_addc_u32 s101, s101, 0
	global_load_dwordx2 v[114:115], v227, s[100:101]
	s_add_u32 s100, s100, 0x1000
	s_addc_u32 s101, s101, 0
	global_load_dwordx2 v[116:117], v227, s[100:101]
	s_add_u32 s100, s100, 0x1000
	s_addc_u32 s101, s101, 0
	global_load_dwordx2 v[118:119], v227, s[100:101]
	s_add_u32 s100, s100, 0x1000
	s_addc_u32 s101, s101, 0
	global_load_dwordx2 v[120:121], v227, s[100:101]
	s_add_u32 s100, s100, 0x1000
	s_addc_u32 s101, s101, 0
	global_load_dwordx2 v[122:123], v227, s[100:101]
	s_add_u32 s100, s100, 0x1000
	s_addc_u32 s101, s101, 0
	global_load_dwordx2 v[124:125], v227, s[100:101]
	s_add_u32 s100, s100, 0x1000
	s_addc_u32 s101, s101, 0
	global_load_dwordx2 v[126:127], v227, s[100:101]
	s_add_u32 s100, s100, 0x1000
	s_addc_u32 s101, s101, 0
	global_load_dwordx2 v[128:129], v227, s[100:101]
	s_add_u32 s100, s100, 0x1000
	s_addc_u32 s101, s101, 0
	global_load_dwordx2 v[130:131], v227, s[100:101]
	s_add_u32 s100, s100, 0x1000
	s_addc_u32 s101, s101, 0
	global_load_dwordx2 v[132:133], v227, s[100:101]
	s_add_u32 s100, s100, 0x1000
	s_addc_u32 s101, s101, 0
	global_load_dwordx2 v[134:135], v227, s[100:101]
	s_add_u32 s100, s100, 0x1000
	s_addc_u32 s101, s101, 0
	global_load_dwordx2 v[136:137], v227, s[100:101]
	s_add_u32 s100, s100, 0x1000
	s_addc_u32 s101, s101, 0
	global_load_dwordx2 v[138:139], v227, s[100:101]
	s_add_u32 s100, s100, 0x1000
	s_addc_u32 s101, s101, 0
	global_load_dwordx2 v[140:141], v227, s[100:101]
	s_add_u32 s100, s100, 0x1000
	s_addc_u32 s101, s101, 0
	global_load_dwordx2 v[142:143], v227, s[100:101]
	s_add_u32 s100, s100, 0x1000
	s_addc_u32 s101, s101, 0
	global_load_dwordx2 v[144:145], v227, s[100:101]
	s_add_u32 s100, s100, 0x1000
	s_addc_u32 s101, s101, 0
	global_load_dwordx2 v[146:147], v227, s[100:101]
	s_add_u32 s100, s100, 0x1000
	s_addc_u32 s101, s101, 0
	global_load_dwordx2 v[148:149], v227, s[100:101]
	s_add_u32 s100, s100, 0x1000
	s_addc_u32 s101, s101, 0
	global_load_dwordx2 v[150:151], v227, s[100:101]
	s_add_u32 s100, s100, 0x1000
	s_addc_u32 s101, s101, 0
	global_load_dwordx2 v[152:153], v227, s[100:101]
	global_load_dwordx2 v[218:219], v227, s[50:51]
	global_load_dwordx2 v[220:221], v227, s[8:9]
	global_load_dwordx2 v[222:223], v227, s[10:11]
	s_and_b32 s4, s6, 0x1fff
	s_cmp_eq_u32 s4, 0
	s_cbranch_scc1 .Lc31_seqstart
; #define LAS __attribute__((address_space(3)))
; __device__ __forceinline__ void conv31_phase(LAS unsigned char* lds, const bf16_t* GLU, bf16_t* SZB, const float* cw, const float* cb, const float* lng, const float* lnb, int G, int c, const int widx) {
;     ...
;         for (int h = 0; h < 2; ++h) {
;             int tf = tid; asm volatile("" : "+v"(tf));
;             u32x4 tv[6];
; #pragma unroll
;             for (int q = 0; q < 6; ++q) { const int i = tf + (h * 6 + q) * 512, r = (i >> 7) < 46 ? (i >> 7) : 45; const int gr = (tpos - 30 + r >= 0) ? (T0 - 30 + r) : T0;
;                 tv[q] = *(const u32x4*)(GLU + (size_t)gr * 1024 + (i & 127) * 8); }
; #pragma unroll
;             for (int q = 0; q < 6; ++q) { const int i = tf + (h * 6 + q) * 512, r = i >> 7;
;                 if (r < 46) *(LAS u32x4*)(lds + ((34 + r) & 63) * 2048 + (i & 127) * 16) = (tpos - 30 + r >= 0) ? tv[q] : (u32x4){0u, 0u, 0u, 0u}; }
;         }
	s_sub_i32 s100, s6, 30
	s_ashr_i32 s101, s100, 31
	s_lshl_b64 s[100:101], s[100:101], 11
	s_add_u32 s100, s100, s14
	s_addc_u32 s101, s101, s15
	global_load_dword v0, v226, s[100:101]
	global_load_dword v2, v226, s[100:101] offset:2048
	s_add_u32 s100, s100, 0x1000
	s_addc_u32 s101, s101, 0
	global_load_dword v4, v226, s[100:101]
	global_load_dword v6, v226, s[100:101] offset:2048
	s_add_u32 s100, s100, 0x1000
	s_addc_u32 s101, s101, 0
	global_load_dword v8, v226, s[100:101]
	global_load_dword v10, v226, s[100:101] offset:2048
	s_add_u32 s100, s100, 0x1000
	s_addc_u32 s101, s101, 0
	global_load_dword v12, v226, s[100:101]
	global_load_dword v14, v226, s[100:101] offset:2048
	s_add_u32 s100, s100, 0x1000
	s_addc_u32 s101, s101, 0
	global_load_dword v16, v226, s[100:101]
	global_load_dword v18, v226, s[100:101] offset:2048
	s_add_u32 s100, s100, 0x1000
	s_addc_u32 s101, s101, 0
	global_load_dword v20, v226, s[100:101]
	global_load_dword v22, v226, s[100:101] offset:2048
	s_add_u32 s100, s100, 0x1000
	s_addc_u32 s101, s101, 0
	global_load_dword v24, v226, s[100:101]
	global_load_dword v26, v226, s[100:101] offset:2048
	s_add_u32 s100, s100, 0x1000
	s_addc_u32 s101, s101, 0
	global_load_dword v28, v226, s[100:101]
	global_load_dword v30, v226, s[100:101] offset:2048
	s_add_u32 s100, s100, 0x1000
	s_addc_u32 s101, s101, 0
	global_load_dword v32, v226, s[100:101]
	global_load_dword v34, v226, s[100:101] offset:2048
	s_add_u32 s100, s100, 0x1000
	s_addc_u32 s101, s101, 0
	global_load_dword v36, v226, s[100:101]
	global_load_dword v38, v226, s[100:101] offset:2048
	s_add_u32 s100, s100, 0x1000
	s_addc_u32 s101, s101, 0
	global_load_dword v40, v226, s[100:101]
	global_load_dword v42, v226, s[100:101] offset:2048
	s_add_u32 s100, s100, 0x1000
	s_addc_u32 s101, s101, 0
	global_load_dword v44, v226, s[100:101]
	global_load_dword v46, v226, s[100:101] offset:2048
	s_add_u32 s100, s100, 0x1000
	s_addc_u32 s101, s101, 0
	global_load_dword v48, v226, s[100:101]
	global_load_dword v50, v226, s[100:101] offset:2048
	s_add_u32 s100, s100, 0x1000
	s_addc_u32 s101, s101, 0
	global_load_dword v52, v226, s[100:101]
	global_load_dword v54, v226, s[100:101] offset:2048
	s_add_u32 s100, s100, 0x1000
	s_addc_u32 s101, s101, 0
	global_load_dword v56, v226, s[100:101]
	global_load_dword v58, v226, s[100:101] offset:2048
	s_add_u32 s100, s100, 0x1000
	s_addc_u32 s101, s101, 0
	global_load_dword v60, v226, s[100:101]
	global_load_dword v62, v226, s[100:101] offset:2048
	s_add_u32 s100, s100, 0x1000
	s_addc_u32 s101, s101, 0
	global_load_dword v64, v226, s[100:101]
	global_load_dword v66, v226, s[100:101] offset:2048
	s_add_u32 s100, s100, 0x1000
	s_addc_u32 s101, s101, 0
	global_load_dword v68, v226, s[100:101]
	global_load_dword v70, v226, s[100:101] offset:2048
	s_add_u32 s100, s100, 0x1000
	s_addc_u32 s101, s101, 0
	global_load_dword v72, v226, s[100:101]
	global_load_dword v74, v226, s[100:101] offset:2048
	s_add_u32 s100, s100, 0x1000
	s_addc_u32 s101, s101, 0
	global_load_dword v76, v226, s[100:101]
	global_load_dword v78, v226, s[100:101] offset:2048
	s_add_u32 s100, s100, 0x1000
	s_addc_u32 s101, s101, 0
	global_load_dword v80, v226, s[100:101]
	global_load_dword v82, v226, s[100:101] offset:2048
	s_add_u32 s100, s100, 0x1000
	s_addc_u32 s101, s101, 0
	global_load_dword v84, v226, s[100:101]
	global_load_dword v86, v226, s[100:101] offset:2048
	s_add_u32 s100, s100, 0x1000
	s_addc_u32 s101, s101, 0
	global_load_dword v88, v226, s[100:101]
	global_load_dword v90, v226, s[100:101] offset:2048
	s_branch .Lc31_filled

;     __device__ __forceinline__ bool next(int i, Unit& u) const {
;         const int L = i * G + c; if (L >= 512) return false;
;         u.pm = L >> 2; u.pn = L & 3; u.kind = 0;
;         u.A = Aq + (size_t)u.pm * TILE + (size_t)u.pn * 512; u.B = Bm + (size_t)(u.pm >> 5) * bstride_b + (size_t)u.pn * bstride_h; return true;
; __global__ void __launch_bounds__(512, 2) fwd_megakernel(Params p) {
;     ...
;         { SchedAttn S{(const char*)Q, (const char*)KB, TILE, (size_t)512, G, bx}; EpiS E{Q, RSUM}; gemm_phase(lds, 1024, 1024, 256, S, E, widx); }
.Lc31_done:
	s_waitcnt lgkmcnt(0)
	s_barrier
	v_mbcnt_lo_u32_b32 v0, -1, 0
	v_mbcnt_hi_u32_b32 v0, -1, v0
	s_cmpk_lt_i32 s2, 0x200
	v_add_u32_e32 v8, s87, v0
	s_cselect_b64 s[4:5], -1, 0
	s_cmpk_gt_i32 s2, 0x1ff
	v_readfirstlane_b32 s6, v8
	s_cbranch_scc1 .LBB0_354
	s_ashr_i32 s28, s2, 2
	s_ashr_i32 s29, s28, 31
	s_and_b32 s30, s2, 3
	s_lshl_b64 s[0:1], s[28:29], 19
	s_add_u32 s0, s46, s0
	s_addc_u32 s1, s47, s1
	s_lshl_b32 s7, s30, 9
	s_add_u32 s74, s0, s7
	s_addc_u32 s75, s1, 0
	s_ashr_i32 s0, s2, 7
	s_ashr_i32 s1, s0, 31
	s_lshl_b64 s[0:1], s[0:1], 19
	s_add_u32 s0, s56, s0
	s_addc_u32 s1, s57, s1
	s_add_u32 s76, s0, s7
	s_addc_u32 s77, s1, 0
	s_branch .LBB0_355

; __global__ void __launch_bounds__(512, 2) fwd_megakernel(Params p) {
;     ...
;     asm volatile("s_waitcnt vmcnt(0) lgkmcnt(0)" ::: "memory"); __syncthreads();
;     __builtin_amdgcn_fence(__ATOMIC_ACQUIRE, "agent"); asm volatile("s_waitcnt vmcnt(0)" ::: "memory"); __syncthreads();
;     { SchedAttn S{(const char*)Q, (const char*)VT, (size_t)1024 * 256 * 2, (size_t)256 * 256 * 2, G, bx}; EpiPV E{SZX, U  , RSUM}; gemm_phase(lds, 1024, 256, 256, S, E, widx); }
.LBB0_385:
.LBB0_458:
	s_waitcnt vmcnt(0) lgkmcnt(0)
	s_barrier
	s_waitcnt vmcnt(0) lgkmcnt(0)
	s_barrier
	buffer_inv sc1
	s_waitcnt vmcnt(0)
	s_barrier
	v_mbcnt_lo_u32_b32 v0, -1, 0
	v_mbcnt_hi_u32_b32 v0, -1, v0
	v_readlane_b32 s66, v255, 4
	v_add_u32_e32 v8, s87, v0
	s_and_b64 vcc, exec, s[0:1]
	v_readfirstlane_b32 s5, v8
	v_readlane_b32 s67, v255, 5
	s_cbranch_vccnz .LBB0_472
	v_lshlrev_b32_e32 v0, 4, v8
	v_add_u32_e32 v1, 0x2000, v0
	v_ashrrev_i32_e32 v2, 31, v1
	v_lshrrev_b32_e32 v2, 22, v2
	v_add_u32_e32 v2, v1, v2
	v_ashrrev_i32_e32 v2, 10, v2
	v_mul_i32_i24_e32 v4, 0x400, v2
	v_sub_u32_e32 v1, v1, v4
	v_lshrrev_b32_e32 v4, 4, v1
	v_bitop3_b32 v1, v4, v1, 32 bitop3:0x6c
	v_ashrrev_i32_e32 v4, 31, v1
	v_lshrrev_b32_e32 v4, 26, v4
	v_add_u32_e32 v4, v1, v4
	v_lshlrev_b32_e32 v3, 5, v2
	v_ashrrev_i32_e32 v5, 6, v4
	v_and_b32_e32 v4, 0xc0, v4
	v_lshlrev_b32_e32 v2, 3, v2
	v_sub_u32_e32 v1, v1, v4
	v_mov_b32_e32 v4, 1
	v_and_b32_e32 v2, -16, v2
	v_and_b32_e32 v3, 32, v3
	v_ashrrev_i16_sdwa v1, v4, sext(v1) dst_sel:DWORD dst_unused:UNUSED_PAD src0_sel:DWORD src1_sel:BYTE_0
	v_add_u32_e32 v2, v5, v2
	v_add_u32_sdwa v1, v3, sext(v1) dst_sel:DWORD dst_unused:UNUSED_PAD src0_sel:DWORD src1_sel:WORD_0
	v_lshlrev_b32_e32 v3, 9, v2
	v_lshl_add_u32 v128, v1, 1, v3
	v_bfe_i32 v3, v8, 27, 1
	v_lshrrev_b32_e32 v3, 22, v3
	v_add_u32_e32 v3, v0, v3
	v_and_b32_e32 v3, 0xfffffc00, v3
	v_sub_u32_e32 v0, v0, v3
	v_lshrrev_b32_e32 v3, 4, v0
	v_ashrrev_i32_e32 v1, 31, v8
	v_bitop3_b32 v0, v3, v0, 32 bitop3:0x6c
	v_lshrrev_b32_e32 v1, 26, v1
	v_ashrrev_i32_e32 v3, 31, v0
	v_add_u32_e32 v1, v8, v1
	v_lshrrev_b32_e32 v3, 26, v3
	s_movk_i32 s7, 0x600
	v_ashrrev_i32_e32 v1, 6, v1
	v_add_u32_e32 v3, v0, v3
	v_mad_u64_u32 v[130:131], s[8:9], v2, s7, v[128:129]
	v_lshlrev_b32_e32 v2, 5, v1
	v_ashrrev_i32_e32 v5, 6, v3
	v_and_b32_e32 v3, 0xc0, v3
	v_lshlrev_b32_e32 v1, 3, v1
	v_sub_u32_e32 v0, v0, v3
	v_and_b32_e32 v1, -16, v1
	v_and_b32_e32 v2, 32, v2
	v_ashrrev_i16_sdwa v0, v4, sext(v0) dst_sel:DWORD dst_unused:UNUSED_PAD src0_sel:DWORD src1_sel:BYTE_0
	v_add_u32_e32 v1, v5, v1
	v_add_u32_sdwa v0, v2, sext(v0) dst_sel:DWORD dst_unused:UNUSED_PAD src0_sel:DWORD src1_sel:WORD_0
	v_lshlrev_b32_e32 v2, 9, v1
	v_lshl_add_u32 v132, v0, 1, v2
	s_ashr_i32 s28, s2, 2
	s_ashr_i32 s10, s5, 6
	v_mad_u64_u32 v[134:135], s[8:9], v1, s7, v[132:133]
	s_ashr_i32 s29, s28, 31
	s_ashr_i32 s6, s5, 8
	s_lshl_b32 s4, s10, 10
	s_and_b32 s78, s2, 3
	s_lshl_b64 s[8:9], s[28:29], 19
	s_add_u32 s7, s46, s8
	s_addc_u32 s8, s47, s9
	s_lshl_b32 s9, s78, 9
	s_add_u32 s60, s7, s9
	s_addc_u32 s61, s8, 0
	s_ashr_i32 s8, s2, 7
	s_ashr_i32 s9, s8, 31
	s_lshl_b64 s[8:9], s[8:9], 19
	s_add_u32 s7, s38, s8
	s_addc_u32 s8, s39, s9
	s_lshl_b32 s9, s78, 17
	s_add_u32 s62, s7, s9
	s_addc_u32 s63, s8, 0
	s_add_i32 s12, s4, 0
	s_add_i32 m0, s12, 0x10000
	v_mov_b32_e32 v133, 0
	global_load_lds_dwordx4 v132, s[62:63]
	s_add_i32 m0, s12, 0x12000
	s_add_u32 s8, s62, 0x10000
	global_load_lds_dwordx4 v128, s[62:63]
	s_addc_u32 s9, s63, 0
	s_add_i32 m0, s12, 0x14000
	s_add_i32 s13, s12, 0x2000
	global_load_lds_dwordx4 v132, s[8:9]
	s_add_i32 m0, s12, 0x16000
	v_mov_b32_e32 v129, v133
	global_load_lds_dwordx4 v128, s[8:9]
	s_mov_b32 m0, s12
	s_add_u32 s8, s60, 0x40000
	global_load_lds_dwordx4 v134, s[60:61]
	s_mov_b32 m0, s13
	s_addc_u32 s9, s61, 0
	s_add_i32 s33, s12, 0x4000
	global_load_lds_dwordx4 v130, s[60:61]
	s_mov_b32 m0, s33
	s_add_i32 s34, s12, 0x6000
	global_load_lds_dwordx4 v134, s[8:9]
	s_mov_b32 m0, s34
	v_mov_b32_e32 v135, v133
	global_load_lds_dwordx4 v130, s[8:9]
	v_mov_b32_e32 v131, v133
	s_cmp_eq_u32 s6, 1
	s_movk_i32 s35, 0x2000
	s_mov_b32 s7, 0
	v_lshl_add_u64 v[6:7], s[62:63], 0, v[132:133]
	v_lshl_add_u64 v[4:5], s[62:63], 0, v[128:129]
	v_lshl_add_u64 v[0:1], s[60:61], 0, v[134:135]
	s_cselect_b64 s[8:9], -1, 0
	s_cmp_lg_u32 s6, 1
	v_lshl_add_u64 v[2:3], s[60:61], 0, v[130:131]
	s_cbranch_scc1 .LBB0_461
	s_barrier
